# v104: v99 + differential-head K-fragment LDS addresses formed before the loop barrier
# baseline (speedup 1.0000x reference)
; #define ATT_WAITV(n) asm volatile("s_waitcnt vmcnt(" #n ")" ::: "memory")
; template <int MODE>
; __device__ __forceinline__ void attn_unit(const Params& P, LAS unsigned char* lds, const int b, const int h, const int qb) {
;     ...
;     const int krow = 4 * w + (lane >> 4), kchunk = (lane & 15) ^ (krow & 15);
;     const bf16_t* kg = Kb_ + (size_t)krow * RS + kchunk * 8;
;     const int vst = 2 * w + (lane >> 5), vkey = (vst >> 2) * 8 + ((lane >> 2) & 7);
;     const bf16_t* vg = Vb_ + (size_t)vkey * RS + (vst & 3) * 32 + (lane & 3) * 8;
;     const float* cg_ = Cl + lane;
;     ...
;     const int pr = (r & 19) | ((r & 4) << 1) | ((r & 8) >> 1);
;     const unsigned kra = pr * 256, kswz = pr & 15;
;     const unsigned vra = 16384 + hh * 2048 + ((lane & 15) >> 2) * 64 + ((lane >> 4) & 1) * 32 + (lane & 3) * 8;
;     f32x16 O[4];
; #pragma unroll
;     for (int d = 0; d < 4; ++d)
; #pragma unroll
;         for (int i = 0; i < 16; ++i) O[d][i] = 0.f;
;     float m1 = ONLINE ? -INFINITY : 0.f, l1 = 0.f;
;     const int ktw_last = (q0w + 31) / 64;
;     ATT_WAITV(0); __builtin_amdgcn_s_barrier(); asm volatile("" ::: "memory");
; #pragma unroll
;     for (int i = 0; i < AL_PD; ++i) if (kt0 + i < nt) ATT_DMA(kt0 + i, i);
;     ...
;                 const unsigned kb_ = (unsigned)(uintptr_t)Kb + kra, c0 = mp * 8 + hh;
;                 k_issue4(kf, kb_ + (((c0) ^ kswz) << 4), kb_ + (((c0 + 2) ^ kswz) << 4), kb_ + (((c0 + 4) ^ kswz) << 4), kb_ + (((c0 + 6) ^ kswz) << 4));
.LBB0_472:
	v_and_b32_e32 v2, 19, v6
	v_lshlrev_b32_e32 v3, 1, v6
	v_and_or_b32 v2, v3, 8, v2
	v_lshrrev_b32_e32 v3, 1, v6
	v_and_b32_e32 v3, 4, v3
	v_or_b32_e32 v4, v2, v3
	v_bitop3_b32 v2, v2, 15, v3 bitop3:0xc8
	v_lshlrev_b32_e32 v3, 4, v6
	v_and_b32_e32 v160, 0xc0, v3
	v_lshl_or_b32 v3, s1, 3, v7
	v_lshlrev_b32_e32 v159, 8, v4
	v_bitop3_b32 v4, v4, v3, 15 bitop3:0x6c
	v_lshlrev_b32_e32 v161, 4, v4
	v_bitop3_b32 v4, v3, v2, 2 bitop3:0x36
	v_lshlrev_b32_e32 v164, 4, v4
	v_bitop3_b32 v4, v3, v2, 4 bitop3:0x36
	v_bitop3_b32 v2, v3, v2, 6 bitop3:0x36
	s_add_i32 s38, s99, s38
	v_lshlrev_b32_e32 v148, 3, v7
	v_lshlrev_b32_e32 v166, 4, v2
	v_add_u32_e32 v2, s38, v8
	v_sub_u32_e32 v167, v2, v148
	v_add_u32_e32 v2, s39, v10
	v_ashrrev_i32_e32 v3, 31, v2
	v_lshlrev_b32_e32 v165, 4, v4
	v_lshlrev_b64 v[2:3], 8, v[2:3]
	v_and_b32_e32 v4, 15, v9
	s_and_b32 s70, s22, -8
	v_bfe_u32 v0, v6, 2, 3
	s_add_i32 s38, s97, s33
	v_lshl_or_b32 v2, v4, 4, v2
	s_add_i32 s40, s38, s98
	v_lshl_add_u64 v[152:153], s[52:53], 0, v[2:3]
	v_add_u32_e32 v2, s70, v0
	s_lshl_b32 s38, s58, 1
	v_ashrrev_i32_e32 v3, 31, v2
	v_and_b32_e32 v0, 3, v6
	s_and_b32 s38, s38, 0x80
	v_lshlrev_b64 v[2:3], 8, v[2:3]
	v_lshlrev_b32_e32 v0, 4, v0
	v_lshl_or_b32 v4, v7, 6, s38
	v_lshlrev_b32_e32 v5, 5, v10
	v_or3_b32 v2, v2, v0, v4
	v_mov_b32_e32 v14, v1
	v_mov_b32_e32 v15, v1
	v_lshlrev_b32_e32 v157, 11, v7
	v_and_b32_e32 v158, 32, v5
	s_add_i32 s22, s99, 0x80
	s_mov_b32 s41, s13
	v_lshl_add_u64 v[154:155], s[52:53], 0, v[2:3]
	v_mov_b32_e32 v0, v1
	v_mov_b32_e32 v2, v1
	v_mov_b32_e32 v3, v1
	v_mov_b32_e32 v4, v1
	v_mov_b32_e32 v5, v1
	v_mov_b32_e32 v6, v1
	v_mov_b32_e32 v7, v1
	v_mov_b32_e32 v8, v1
	v_mov_b32_e32 v9, v1
	v_mov_b32_e32 v10, v1
	v_mov_b32_e32 v11, v1
	v_mov_b32_e32 v12, v1
	v_mov_b32_e32 v13, v1
	v_mov_b64_e32 v[30:31], v[14:15]
	v_mov_b64_e32 v[46:47], v[14:15]
	v_mov_b64_e32 v[62:63], v[14:15]
	v_mov_b64_e32 v[78:79], v[14:15]
	v_lshlrev_b32_e32 v149, 7, v162
	s_lshr_b32 s22, s22, 6
	s_lshr_b32 s23, s59, 6
	s_add_i32 s75, s59, 0xffffff41
	s_lshl_b64 s[68:69], s[40:41], 21
	s_mov_b32 s38, 0
	v_mov_b32_e32 v163, 0
	s_mov_b32 s39, 63
	v_mov_b64_e32 v[28:29], v[12:13]
	v_mov_b64_e32 v[26:27], v[10:11]
	v_mov_b64_e32 v[24:25], v[8:9]
	v_mov_b64_e32 v[22:23], v[6:7]
	v_mov_b64_e32 v[20:21], v[4:5]
	v_mov_b64_e32 v[18:19], v[2:3]
	v_mov_b64_e32 v[16:17], v[0:1]
	v_mov_b64_e32 v[44:45], v[12:13]
	v_mov_b64_e32 v[42:43], v[10:11]
	v_mov_b64_e32 v[40:41], v[8:9]
	v_mov_b64_e32 v[38:39], v[6:7]
	v_mov_b64_e32 v[36:37], v[4:5]
	v_mov_b64_e32 v[34:35], v[2:3]
	v_mov_b64_e32 v[32:33], v[0:1]
	v_mov_b64_e32 v[60:61], v[12:13]
	v_mov_b64_e32 v[58:59], v[10:11]
	v_mov_b64_e32 v[56:57], v[8:9]
	v_mov_b64_e32 v[54:55], v[6:7]
	v_mov_b64_e32 v[52:53], v[4:5]
	v_mov_b64_e32 v[50:51], v[2:3]
	v_mov_b64_e32 v[48:49], v[0:1]
	v_mov_b64_e32 v[76:77], v[12:13]
	v_mov_b64_e32 v[74:75], v[10:11]
	v_mov_b64_e32 v[72:73], v[8:9]
	v_mov_b64_e32 v[70:71], v[6:7]
	v_mov_b64_e32 v[68:69], v[4:5]
	v_mov_b64_e32 v[66:67], v[2:3]
	v_mov_b64_e32 v[64:65], v[0:1]
	s_mov_b32 s38, 0
	s_and_b32 s41, s38, 0x18000
	s_addk_i32 s41, 0x100
	v_add_u32_e32 v202, s41, v159
	v_add_u32_e32 v203, v202, v161
	v_add_u32_e32 v204, v202, v164
	v_add_u32_e32 v205, v202, v165
	v_add_u32_e32 v206, v202, v166
	s_mov_b32 s40, 0
	s_waitcnt vmcnt(0)
	s_branch .LBB0_475

; #define ATT_WAITV(n) asm volatile("s_waitcnt vmcnt(" #n ")" ::: "memory")
; template <int MODE>
; __device__ __forceinline__ void attn_unit(const Params& P, LAS unsigned char* lds, const int b, const int h, const int qb) {
;     ...
;     for (int kt = kt0; kt < nt; ++kt) {
;         const int rel = kt - kt0, cur = rel & (AL_NBUF - 1);
;         if (kt + 2 < nt) { if (FOX) ATT_WAITV(10); else ATT_WAITV(8); } else if (kt + 1 < nt) { if (FOX) ATT_WAITV(5); else ATT_WAITV(4); } else ATT_WAITV(0);
;         __builtin_amdgcn_s_barrier(); asm volatile("" ::: "memory");
;         if (kt + AL_PD < nt) ATT_DMA(kt + AL_PD, (rel + AL_PD) & (AL_NBUF - 1));
;     ...
;                 const unsigned kb_ = (unsigned)(uintptr_t)Kb + kra, c0 = mp * 8 + hh;
;                 k_issue4(kf, kb_ + (((c0) ^ kswz) << 4), kb_ + (((c0 + 2) ^ kswz) << 4), kb_ + (((c0 + 4) ^ kswz) << 4), kb_ + (((c0 + 6) ^ kswz) << 4));
.LBB0_474:
	s_add_i32 s40, s40, 1
	s_add_i32 s38, s38, 0x8000
	s_and_b32 s41, s38, 0x18000
	s_addk_i32 s41, 0x100
	v_add_u32_e32 v202, s41, v159
	v_add_u32_e32 v203, v202, v161
	v_add_u32_e32 v204, v202, v164
	v_add_u32_e32 v205, v202, v165
	v_add_u32_e32 v206, v202, v166
	s_add_i32 s39, s39, 64
	v_subrev_u32_e32 v167, 64, v167
	v_lshl_add_u64 v[152:153], v[152:153], 0, s[30:31]
	s_cmp_eq_u32 s22, s40
	v_lshl_add_u64 v[154:155], v[154:155], 0, s[30:31]
	s_cbranch_scc1 .LBB0_490

; #define LAS __attribute__((address_space(3)))
; template <int MODE>
; __device__ __forceinline__ void attn_unit(const Params& P, LAS unsigned char* lds, const int b, const int h, const int qb) {
;     ...
;         if (kt <= ktw_last) {
;             const LAS unsigned char* Kb = lds + cur * 32768;
;             const int kbase = kt * 64 + 8 * hh;
;             u32x4 pk1[4];
;             f32x16 s[2];
; #pragma unroll
;             for (int i = 0; i < 16; ++i) { s[0][i] = 0.f; s[1][i] = 0.f; }
;             s16x4 va[8], vb[8], vc[8], vd[8];
;             const unsigned vaddr = (unsigned)(uintptr_t)(Kb + vra);
;             if constexpr (MODE == 1) {
;                 bf16x8 kf[8];
;                 const unsigned kb_ = (unsigned)(uintptr_t)Kb + kra, c0 = mp * 8 + hh;
;                 k_issue4(kf, kb_ + (((c0) ^ kswz) << 4), kb_ + (((c0 + 2) ^ kswz) << 4), kb_ + (((c0 + 4) ^ kswz) << 4), kb_ + (((c0 + 6) ^ kswz) << 4));
;                 v_issue<0>(va, vaddr);
;                 k_wait<8>(kf);
.LBB0_485:
	s_cmp_gt_u32 s40, s23
	s_cbranch_scc1 .Lm1_skip
	s_and_b32 s41, s38, 0x18000
	s_addk_i32 s41, 0x100
	v_add_u32_e32 v0, s41, v157
	v_add3_u32 v0, v0, v160, v158
	ds_read_b128 v[2:5], v203
	ds_read_b128 v[6:9], v203 offset:8192
	ds_read_b128 v[10:13], v204
	ds_read_b128 v[128:131], v204 offset:8192
	ds_read_b128 v[168:171], v205
	ds_read_b128 v[172:175], v205 offset:8192
	ds_read_b128 v[180:183], v206
	ds_read_b128 v[184:187], v206 offset:8192
	v_add3_u32 v0, v0, v156, s73
	ds_read_b64_tr_b16 v[144:145], v0 offset:0
	ds_read_b64_tr_b16 v[146:147], v0 offset:0x100
	ds_read_b64_tr_b16 v[140:141], v0 offset:0x200
	ds_read_b64_tr_b16 v[142:143], v0 offset:0x300
	ds_read_b64_tr_b16 v[136:137], v0 offset:0x400
	ds_read_b64_tr_b16 v[138:139], v0 offset:0x500
	ds_read_b64_tr_b16 v[132:133], v0 offset:0x600
	ds_read_b64_tr_b16 v[134:135], v0 offset:0x700
	s_waitcnt lgkmcnt(8)
	s_sub_i32 s41, s39, 63
	s_cmp_le_i32 s41, s75
	s_cbranch_scc0 .Lm1_slow
	s_cmp_le_u32 s39, s59
	s_cbranch_scc1 .Lm1_fast
